# RG-LRU prompt units run inside phase +3: 25% of WG blocks [conv,attn,attn,LRU], 75% [LRU,attn,attn,conv]; phase +5 = sample scan + post
# baseline (speedup 1.0000x reference)
; #define SUB(k, bit) (!(kargs()->li == 1 && (k) == lo) || ((kargs()->submask >> (bit)) & 1u))
; __global__ void __launch_bounds__(NWAVES * 64, 2) fwd(Args args_unused) {
;     ...
;         if (IN(pb + 3)) {
;             PH_PTRS PH_LAYER
;             if (SUB(pb + 3, 0)) {
.LBB0_1364:
	v_readlane_b32 s99, v254, 3
	s_nop 3
	s_lshr_b32 s99, s99, 3
	s_and_b32 s99, s99, 3
	s_mov_b32 s98, 2
	s_cmp_eq_u32 s99, 1
	s_cselect_b32 s98, 0, s98
	s_cmp_eq_u32 s99, 2
	s_cselect_b32 s98, 0, s98
	s_cmp_eq_u32 s99, 3
	s_cselect_b32 s98, 0, s98
	s_mov_b32 s100, 0
	s_mov_b32 s101, 0
.Lmx_again_0:
	s_cmp_lg_u32 s98, 0
	s_cbranch_scc1 .Lmx_go_0
	s_cmp_lg_u32 s100, 0
	s_cbranch_scc1 .Lmx_go_0
	s_mov_b32 s101, 2
	s_branch .LBB0_1808
.Lmx_retB_0:
	s_mov_b32 s100, 1
	s_mov_b32 s101, 0
	s_branch .Lmx_again_0

; #define SEAM(k) do { if (IN(k) && IN((k) + 1)) { KArgs Ab = kargs(); XcdBarrier bar_; bar_.bar = (unsigned*)(Ab->ws + WS_CTL) + CW_BAR + Ab->li * XCD_BAR_WORDS; bar_.x = xb_xcc_id(); bar_.st = MISC + 8; xcd_barrier(bar_, (int)threadIdx.x); } } while (0)
; __global__ void __launch_bounds__(NWAVES * 64, 2) fwd(Args args_unused) {
;     ...
;             }
;         }
;         SEAM(pb + 3);
.Lmx_fin_0:
	s_cmp_lg_u32 s100, 0
	s_cbranch_scc1 .Lmx_done_0
	s_mov_b32 s101, 1
	s_branch .LBB0_1808
.Lmx_retA_0:
	s_mov_b32 s100, 1
	s_mov_b32 s101, 0

; #define LAS __attribute__((address_space(3)))
; #define SUB(k, bit) (!(kargs()->li == 1 && (k) == lo) || ((kargs()->submask >> (bit)) & 1u))
; __global__ void __launch_bounds__(NWAVES * 64, 2) fwd(Args args_unused) {
;     ...
;         if (IN(pb + 5)) {
;             PH_PTRS PH_LAYER
;             if (SUB(pb + 5, 0)) {
;                 constexpr int LT = 136, AS = 68;
;                 LAS bf16* Xs = (LAS bf16*)lds;
;                 LAS bf16* Ws = Xs + 128 * LT;
;                 LAS float* As = (LAS float*)(Ws + 128 * LT);
;                 LAS float* Us = As + 128 * AS;
;                 LAS float* sP = Us + 128 * AS;
;                 LAS float* sH = sP + 512;
;                 LAS float* cS = sH + 512;
;                 LAS float* cst = cS + 128;
;                 static_assert(2 * 128 * LT * 2 + (2 * 128 * AS + 512 + 512 + 128 + 192) * 4 <= LDSCTL_OFF, "LRU LDS map");
;                 const int qq = lane & 15, q4 = lane >> 4, w = wave;
;                 for (int un = vcu; un < 256; un += G) {
;                     const int b = un >> 4, j = (un >> 1) & 7, h2 = un & 1, chb = j * 128 + 64 * h2;
;                     __syncthreads();
;                     { const bf16* wg = (const bf16*)(wl + WL_G);
; #pragma unroll
;                       for (int k = 0; k < 4; ++k) { const int idx = tid + 512 * k, n = idx >> 4, part = idx & 15; const int srow = j * 256 + (n < 64 ? 64 * h2 + n : 128 + 64 * h2 + (n - 64));
;                           *(LAS v4u*)(Ws + n * LT + part * 8) = *(const v4u*)(wg + (size_t)srow * 128 + part * 8); }
;                       if (tid < 64) { cst[tid] = A->in[I_BR][l * DM + chb + tid]; cst[64 + tid] = A->in[I_BI][l * DM + chb + tid]; cst[128 + tid] = ((const float*)(ws + WS_SPL))[l * DM + chb + tid]; cS[tid] = 0.f; } }
;                     const int cpart = tid & 15, ctb = 4 * (tid >> 4);
;                     float cwv[4][8], cbv[8];
; #pragma unroll
;                     for (int e = 0; e < 8; ++e) { cbv[e] = A->in[I_CCB][l * DM + j * 128 + cpart * 8 + e];
; #pragma unroll
;                         for (int jj = 0; jj < 4; ++jj) cwv[jj][e] = A->in[I_CCW][(size_t)(l * 4 + jj) * DM + j * 128 + cpart * 8 + e]; }
;                     v4u xr[7] = {(v4u){0u, 0u, 0u, 0u}, (v4u){0u, 0u, 0u, 0u}, (v4u){0u, 0u, 0u, 0u}, (v4u){0u, 0u, 0u, 0u}, (v4u){0u, 0u, 0u, 0u}, (v4u){0u, 0u, 0u, 0u}, (v4u){0u, 0u, 0u, 0u}};
;     ...
;                     LRU_LOAD(0);
.LBB0_1808:
	s_cmp_lt_i32 s84, 9
	s_cselect_b64 s[4:5], -1, 0
	s_and_b64 s[0:1], s[4:5], s[0:1]
	s_andn2_b64 vcc, exec, s[0:1]
	s_cbranch_vccnz .LBB0_1930
	s_mov_b64 s[34:35], s[82:83]
	s_load_dwordx4 s[28:31], s[34:35], 0x140
	s_mov_b32 s6, 0
	s_load_dword s3, s[82:83], 0x168
	v_readlane_b32 s33, v254, 3
	s_mov_b32 s63, s2
	v_mov_b32_e32 v126, v0
	s_waitcnt lgkmcnt(0)
	s_add_u32 s26, s30, 0x1d200000
	s_addc_u32 s27, s31, 0
	v_ashrrev_i32_e32 v144, 6, v126
	s_mov_b32 s41, 0
	v_and_b32_e32 v1, 63, v126
	s_cmpk_gt_i32 s33, 0xff
	v_readfirstlane_b32 s62, v144
	s_cselect_b32 s99, 1, 0
	s_cmp_eq_u32 s101, 0
	s_cbranch_scc1 .LBB0_1918
	s_cmp_lg_u32 s99, 0
	s_cbranch_scc1 .LBB0_1918
	v_lshlrev_b32_e32 v2, 4, v126
	v_and_b32_e32 v4, 0xf0, v2
	v_mov_b32_e32 v2, 0
	v_and_b32_e32 v3, 15, v126
	v_mov_b32_e32 v5, v2
	v_lshlrev_b32_e32 v8, 3, v126
	v_lshl_add_u64 v[6:7], s[30:31], 0, v[4:5]
	s_mov_b64 s[4:5], 0x4300000
	v_lshl_or_b32 v5, s62, 4, v3
	s_movk_i32 s47, 0x110
	s_add_i32 s7, s6, 0x22000
	s_add_i32 s40, s6, 0x22800
	s_add_i32 s64, s6, 0x23000
	s_add_i32 s44, s6, 0x23200
	v_lshl_add_u64 v[128:129], v[6:7], 0, s[4:5]
	v_add_u32_e32 v6, s6, v4
	v_lshlrev_b32_e32 v4, 2, v126
	v_and_b32_e32 v150, 56, v8
	v_mul_lo_u32 v8, v5, s47
	v_lshrrev_b32_e32 v5, 2, v126
	v_add_u32_e32 v145, s44, v4
	v_add_u32_e32 v146, s64, v4
	v_and_b32_e32 v13, 12, v5
	v_add_u32_e32 v153, s7, v4
	v_add_u32_e32 v154, s40, v4
	v_lshlrev_b32_e32 v4, 1, v150
	v_mov_b32_e32 v5, v2
	v_lshl_add_u64 v[4:5], s[30:31], 0, v[4:5]
	s_mov_b64 s[10:11], 0x79f00000
	s_add_i32 s45, s6, 0x19800
	s_add_i32 s46, s6, 0x11000
	v_lshl_add_u64 v[132:133], v[4:5], 0, s[10:11]
	v_add_u32_e32 v5, 0x200, v126
	s_add_u32 s42, s30, 0xb080000
	v_ashrrev_i32_e32 v156, 4, v5
	v_ashrrev_i32_e32 v136, 3, v5
	v_lshlrev_b32_e32 v5, 2, v13
	s_addc_u32 s43, s31, 0
	v_add_u32_e32 v151, s6, v8
	s_add_i32 s48, s6, 0x23300
	s_add_i32 s49, s6, 0x23400
	v_add3_u32 v162, s46, v8, v5
	v_add3_u32 v163, s45, v8, v5
	v_or_b32_e32 v8, 64, v5
	v_add_u32_e32 v159, s44, v5
	v_add_u32_e32 v160, s48, v5
	v_add_u32_e32 v161, s49, v5
	v_add_u32_e32 v164, s44, v8
	v_add_u32_e32 v165, s48, v8
	v_add_u32_e32 v166, s49, v8
	v_or_b32_e32 v8, 0x80, v5
	v_or_b32_e32 v5, 0xc0, v5
	v_add_u32_e32 v167, s44, v8
	v_add_u32_e32 v170, s44, v5
	s_movk_i32 s44, 0x440
	v_add_u32_e32 v171, s48, v5
	v_add_u32_e32 v172, s49, v5
	v_mul_lo_u32 v5, v144, s44
	v_or_b32_e32 v5, v5, v1
	v_lshlrev_b32_e32 v5, 2, v5
	v_add_u32_e32 v173, s46, v5
	v_add_u32_e32 v174, s45, v5
	v_lshl_or_b32 v5, v144, 4, 1
	s_movk_i32 s44, 0x44
	v_add_u32_e32 v168, s48, v8
	v_add_u32_e32 v169, s49, v8
	v_mul_lo_u32 v8, v5, s44
	v_lshlrev_b32_e32 v10, 2, v1
	v_add_u32_e32 v19, v8, v1
	v_add_u32_e32 v14, s45, v10
	v_lshl_add_u32 v175, v19, 2, s46
	v_add_u32_e32 v19, 0x44, v8
	v_add_u32_e32 v20, v19, v1
	v_lshl_add_u32 v178, v19, 2, v14
	v_add_u32_e32 v19, 0x88, v8
	v_lshl_add_u32 v177, v20, 2, s46
	v_add_u32_e32 v20, v19, v1
	v_lshl_add_u32 v180, v19, 2, v14
	v_add_u32_e32 v19, 0xcc, v8
	v_lshl_add_u32 v179, v20, 2, s46
	v_add_u32_e32 v20, v19, v1
	v_lshl_add_u32 v182, v19, 2, v14
	v_add_u32_e32 v19, 0x110, v8
	v_lshl_add_u32 v181, v20, 2, s46
	v_add_u32_e32 v20, v19, v1
	v_lshl_add_u32 v184, v19, 2, v14
	v_add_u32_e32 v19, 0x154, v8
	v_lshl_add_u32 v183, v20, 2, s46
	v_add_u32_e32 v20, v19, v1
	v_lshl_add_u32 v186, v19, 2, v14
	v_add_u32_e32 v19, 0x198, v8
	v_lshl_add_u32 v185, v20, 2, s46
	v_add_u32_e32 v20, v19, v1
	v_lshl_add_u32 v188, v19, 2, v14
	v_add_u32_e32 v19, 0x1dc, v8
	v_lshl_add_u32 v187, v20, 2, s46
	v_add_u32_e32 v20, v19, v1
	v_lshl_add_u32 v190, v19, 2, v14
	v_add_u32_e32 v19, 0x220, v8
	v_lshl_add_u32 v189, v20, 2, s46
	v_add_u32_e32 v20, v19, v1
	v_lshl_add_u32 v192, v19, 2, v14
	v_add_u32_e32 v19, 0x264, v8
	v_lshl_add_u32 v191, v20, 2, s46
	v_add_u32_e32 v20, v19, v1
	v_lshl_add_u32 v194, v19, 2, v14
	v_add_u32_e32 v19, 0x2a8, v8
	v_lshl_add_u32 v193, v20, 2, s46
	v_add_u32_e32 v20, v19, v1
	v_lshl_add_u32 v196, v19, 2, v14
	v_add_u32_e32 v19, 0x2ec, v8
	s_load_dwordx4 s[36:39], s[34:35], 0xd8
	v_lshl_add_u32 v195, v20, 2, s46
	v_add_u32_e32 v20, v19, v1
	v_lshl_add_u32 v198, v19, 2, v14
	v_add_u32_e32 v19, 0x330, v8
	v_ashrrev_i32_e32 v7, 2, v126
	v_add_u32_e32 v17, 0x400, v126
	v_add_u32_e32 v18, 0x600, v126
	v_lshl_add_u32 v176, v8, 2, v14
	v_lshl_add_u32 v197, v20, 2, s46
	v_add_u32_e32 v20, v19, v1
	v_lshl_add_u32 v200, v19, 2, v14
	v_add_u32_e32 v19, 0x374, v8
	v_add_u32_e32 v8, 0x3b8, v8
	v_and_b32_e32 v9, -4, v7
	v_and_b32_e32 v152, 48, v126
	v_ashrrev_i32_e32 v155, 4, v126
	v_ashrrev_i32_e32 v157, 4, v17
	v_ashrrev_i32_e32 v158, 4, v18
	v_cmp_lt_i32_e64 s[18:19], 3, v7
	v_cmp_lt_i32_e64 s[20:21], -1, v7
	v_or_b32_e32 v7, 3, v7
	v_ashrrev_i32_e32 v134, 3, v126
	v_lshl_add_u32 v199, v20, 2, s46
	v_add_u32_e32 v20, v19, v1
	v_lshl_add_u32 v202, v19, 2, v14
	v_add_u32_e32 v19, v8, v1
	s_movk_i32 s44, 0x1100
	v_lshlrev_b32_e32 v147, 3, v3
	v_add_u32_e32 v130, -3, v9
	v_lshl_add_u32 v11, v3, 4, s6
	v_add_u32_e32 v149, 0x7d, v9
	v_add_u32_e32 v12, s6, v152
	v_lshl_add_u32 v15, v150, 2, s45
	v_mul_lo_u32 v4, v155, s47
	v_mul_lo_u32 v16, v156, s47
	v_mul_lo_u32 v17, v157, s47
	v_mul_lo_u32 v18, v158, s47
	v_cmp_lt_i32_e64 s[22:23], -2, v9
	v_cmp_lt_i32_e64 s[24:25], -3, v9
	v_mul_lo_u32 v9, v9, s47
	v_mul_lo_u32 v7, v7, s47
	v_mul_u32_u24_e32 v3, 0x110, v3
	v_lshl_add_u32 v201, v20, 2, s46
	v_lshl_add_u32 v203, v19, 2, s46
	v_lshl_add_u32 v204, v8, 2, v14
	v_mul_lo_u32 v8, v144, s44
	v_mul_lo_u32 v5, v5, s47
	v_mul_lo_u32 v19, v134, s47
	v_mul_lo_u32 v20, v136, s47
	v_cmp_gt_i32_e64 s[4:5], 64, v126
	v_ashrrev_i32_e32 v131, 31, v130
	v_add_u32_e32 v148, s64, v10
	v_cmp_lt_i32_e64 s[6:7], 0, v144
	v_cmp_eq_u32_e64 s[8:9], 7, v144
	v_ashrrev_i32_e32 v127, 31, v126
	v_cmp_gt_i32_e64 s[10:11], 64, v155
	v_cmp_gt_i32_e64 s[12:13], 64, v156
	v_cmp_gt_i32_e64 s[14:15], 64, v157
	v_cmp_gt_i32_e64 s[16:17], 64, v158
	v_ashrrev_i32_e32 v135, 31, v134
	v_ashrrev_i32_e32 v137, 31, v136
	v_lshl_add_u32 v205, v13, 1, v151
	v_add_u32_e32 v206, s40, v10
	v_add_u32_e32 v207, v6, v4
	v_add_u32_e32 v208, v6, v16
	v_add_u32_e32 v209, v6, v17
	v_add_u32_e32 v210, v6, v18
	s_mov_b64 s[44:45], 0x1000
	s_mov_b64 s[46:47], 0x2000
	s_mov_b64 s[48:49], 0x3000
	v_add_u32_e32 v211, v11, v9
	v_add_u32_e32 v212, v11, v7
	v_add_u32_e32 v213, v12, v3
	s_mov_b32 s65, 0xbecccccd
	v_mov_b32_e32 v214, 0x3c088889
	v_add_u32_e32 v215, v14, v8
	v_add_u32_e32 v216, v14, v5
	v_add_u32_e32 v217, v15, v19
	v_add_u32_e32 v218, v15, v20
	s_mov_b32 s66, s33
	s_branch .LBB0_1812

; __device__ __forceinline__ unsigned f2bf(float f) { return pk2(f, 0.f) & 0xffffu; }
; __device__ __forceinline__ float gelu_tanh(float x) { const float t = 0.7978845608028654f * (x + 0.044715f * x * x * x); return x * rcpf_(1.f + __expf(-2.f * t)); }
; __global__ void __launch_bounds__(NWAVES * 64, 2) fwd(Args args_unused) {
;     ...
;                 }
;                 __syncthreads();
;                 for (int i = bx * 512 + tid; i < 32 * DM; i += G * 512) { const int sb = i >> 10, ch = i & 1023; const size_t r0 = (size_t)NPROMPT + sb * 8;
;                     float hc = A->in[I_SLRU][(size_t)(l * 32 + sb) * DM + ch];
;                     for (int t = 0; t < 8; ++t) { hc = AL[(size_t)(sb * 8 + t) * DM + ch] * hc + U[(size_t)(sb * 8 + t) * DM + ch]; HCG[(r0 + t) * DM + ch] = (bf16)f2bf(hc * gelu_tanh(bf2f(*ZP(Z, r0 + t, ZGC + ch)))); }
.LBB0_1918:
	s_cmp_eq_u32 s101, 1
	s_cbranch_scc1 .Lmx_retA_0
	s_cmp_eq_u32 s101, 2
	s_cbranch_scc1 .Lmx_retB_0
	v_lshl_add_u32 v3, s63, 9, v126
	s_mov_b32 s4, 0x8000
	v_cmp_gt_i32_e32 vcc, s4, v3
	s_waitcnt vmcnt(0)
	s_barrier
	s_and_saveexec_b64 s[4:5], vcc
	s_cbranch_execz .LBB0_1923
	s_load_dwordx2 s[6:7], s[34:35], 0x50
	s_lshl_b32 s8, s63, 9
	v_mov_b32_e32 v2, 1
	s_lshl_b32 s16, s3, 9
	v_add_u16_e32 v7, s8, v126
	v_lshlrev_b32_sdwa v2, v2, v126 dst_sel:DWORD dst_unused:UNUSED_PAD src0_sel:DWORD src1_sel:BYTE_0
	v_mov_b32_e32 v5, 0
	s_mov_b64 s[8:9], 0
	s_mov_b32 s17, 0x7df00000
	s_mov_b32 s18, 0x63d01000
	s_mov_b32 s19, 0x63f01000
	s_mov_b64 s[10:11], 0x2000
	s_mov_b64 s[12:13], 0x1000
	s_mov_b64 s[14:15], 0x400
	s_movk_i32 s20, 0x7fff

; #define LAS __attribute__((address_space(3)))
; #define SUB(k, bit) (!(kargs()->li == 1 && (k) == lo) || ((kargs()->submask >> (bit)) & 1u))
; __global__ void __launch_bounds__(NWAVES * 64, 2) fwd(Args args_unused) {
;     ...
;         if (IN(pb + 5)) {
;             PH_PTRS PH_LAYER
;             if (SUB(pb + 5, 0)) {
;                 constexpr int LT = 136, AS = 68;
;                 LAS bf16* Xs = (LAS bf16*)lds;
;                 LAS bf16* Ws = Xs + 128 * LT;
;                 LAS float* As = (LAS float*)(Ws + 128 * LT);
;                 LAS float* Us = As + 128 * AS;
;                 LAS float* sP = Us + 128 * AS;
;                 LAS float* sH = sP + 512;
;                 LAS float* cS = sH + 512;
;                 LAS float* cst = cS + 128;
;                 static_assert(2 * 128 * LT * 2 + (2 * 128 * AS + 512 + 512 + 128 + 192) * 4 <= LDSCTL_OFF, "LRU LDS map");
;                 const int qq = lane & 15, q4 = lane >> 4, w = wave;
;                 for (int un = vcu; un < 256; un += G) {
;                     const int b = un >> 4, j = (un >> 1) & 7, h2 = un & 1, chb = j * 128 + 64 * h2;
;                     __syncthreads();
;                     { const bf16* wg = (const bf16*)(wl + WL_G);
; #pragma unroll
;                       for (int k = 0; k < 4; ++k) { const int idx = tid + 512 * k, n = idx >> 4, part = idx & 15; const int srow = j * 256 + (n < 64 ? 64 * h2 + n : 128 + 64 * h2 + (n - 64));
;                           *(LAS v4u*)(Ws + n * LT + part * 8) = *(const v4u*)(wg + (size_t)srow * 128 + part * 8); }
;                       if (tid < 64) { cst[tid] = A->in[I_BR][l * DM + chb + tid]; cst[64 + tid] = A->in[I_BI][l * DM + chb + tid]; cst[128 + tid] = ((const float*)(ws + WS_SPL))[l * DM + chb + tid]; cS[tid] = 0.f; } }
;                     const int cpart = tid & 15, ctb = 4 * (tid >> 4);
;                     float cwv[4][8], cbv[8];
; #pragma unroll
;                     for (int e = 0; e < 8; ++e) { cbv[e] = A->in[I_CCB][l * DM + j * 128 + cpart * 8 + e];
; #pragma unroll
;                         for (int jj = 0; jj < 4; ++jj) cwv[jj][e] = A->in[I_CCW][(size_t)(l * 4 + jj) * DM + j * 128 + cpart * 8 + e]; }
;                     v4u xr[7] = {(v4u){0u, 0u, 0u, 0u}, (v4u){0u, 0u, 0u, 0u}, (v4u){0u, 0u, 0u, 0u}, (v4u){0u, 0u, 0u, 0u}, (v4u){0u, 0u, 0u, 0u}, (v4u){0u, 0u, 0u, 0u}, (v4u){0u, 0u, 0u, 0u}};
;     ...
;                     LRU_LOAD(0);
.LBB0_3832:
	s_cmp_lt_i32 s84, 19
	s_cselect_b64 s[4:5], -1, 0
	s_and_b64 s[0:1], s[4:5], s[0:1]
	s_andn2_b64 vcc, exec, s[0:1]
	s_cbranch_vccnz .LBB0_3954
	s_mov_b64 s[34:35], s[82:83]
	s_load_dwordx4 s[28:31], s[34:35], 0x140
	s_mov_b32 s6, 0
	s_mov_b32 s63, s2
	s_load_dword s3, s[82:83], 0x168
	v_readlane_b32 s33, v254, 3
	v_mov_b32_e32 v126, v0
	s_waitcnt lgkmcnt(0)
	s_add_u32 s26, s30, 0x1d200000
	s_addc_u32 s27, s31, 0
	v_ashrrev_i32_e32 v144, 6, v126
	s_mov_b32 s41, 0
	v_and_b32_e32 v1, 63, v126
	s_cmpk_gt_i32 s33, 0xff
	v_readfirstlane_b32 s62, v144
	s_cselect_b32 s99, 1, 0
	s_cmp_eq_u32 s101, 0
	s_cbranch_scc1 .LBB0_3942
	s_cmp_lg_u32 s99, 0
	s_cbranch_scc1 .LBB0_3942
	v_lshlrev_b32_e32 v2, 4, v126
	v_and_b32_e32 v4, 0xf0, v2
	v_mov_b32_e32 v2, 0
	v_and_b32_e32 v3, 15, v126
	v_mov_b32_e32 v5, v2
	v_lshlrev_b32_e32 v8, 3, v126
	v_lshl_add_u64 v[6:7], s[30:31], 0, v[4:5]
	s_mov_b64 s[4:5], 0x8800000
	v_lshl_or_b32 v5, s62, 4, v3
	s_movk_i32 s47, 0x110
	s_add_i32 s7, s6, 0x22000
	s_add_i32 s40, s6, 0x22800
	s_add_i32 s64, s6, 0x23000
	s_add_i32 s44, s6, 0x23200
	v_lshl_add_u64 v[128:129], v[6:7], 0, s[4:5]
	v_add_u32_e32 v6, s6, v4
	v_lshlrev_b32_e32 v4, 2, v126
	v_and_b32_e32 v153, 56, v8
	v_mul_lo_u32 v8, v5, s47
	v_lshrrev_b32_e32 v5, 2, v126
	v_add_u32_e32 v146, s44, v4
	v_add_u32_e32 v147, s64, v4
	v_and_b32_e32 v13, 12, v5
	v_add_u32_e32 v156, s7, v4
	v_add_u32_e32 v157, s40, v4
	v_lshlrev_b32_e32 v4, 1, v153
	v_mov_b32_e32 v5, v2
	v_lshl_add_u64 v[4:5], s[30:31], 0, v[4:5]
	s_mov_b64 s[10:11], 0x79f00000
	s_add_i32 s45, s6, 0x19800
	s_add_i32 s46, s6, 0x11000
	v_lshl_add_u64 v[132:133], v[4:5], 0, s[10:11]
	v_add_u32_e32 v5, 0x200, v126
	s_add_u32 s42, s30, 0xb080000
	v_ashrrev_i32_e32 v159, 4, v5
	v_ashrrev_i32_e32 v136, 3, v5
	v_lshlrev_b32_e32 v5, 2, v13
	s_addc_u32 s43, s31, 0
	v_add_u32_e32 v154, s6, v8
	s_add_i32 s48, s6, 0x23300
	s_add_i32 s49, s6, 0x23400
	v_add3_u32 v165, s46, v8, v5
	v_add3_u32 v166, s45, v8, v5
	v_or_b32_e32 v8, 64, v5
	v_add_u32_e32 v162, s44, v5
	v_add_u32_e32 v163, s48, v5
	v_add_u32_e32 v164, s49, v5
	v_add_u32_e32 v167, s44, v8
	v_add_u32_e32 v168, s48, v8
	v_add_u32_e32 v169, s49, v8
	v_or_b32_e32 v8, 0x80, v5
	v_or_b32_e32 v5, 0xc0, v5
	v_add_u32_e32 v170, s44, v8
	v_add_u32_e32 v173, s44, v5
	s_movk_i32 s44, 0x440
	v_add_u32_e32 v174, s48, v5
	v_add_u32_e32 v175, s49, v5
	v_mul_lo_u32 v5, v144, s44
	v_or_b32_e32 v5, v5, v1
	v_lshlrev_b32_e32 v5, 2, v5
	v_add_u32_e32 v176, s46, v5
	v_add_u32_e32 v177, s45, v5
	v_lshl_or_b32 v5, v144, 4, 1
	s_movk_i32 s44, 0x44
	v_add_u32_e32 v171, s48, v8
	v_add_u32_e32 v172, s49, v8
	v_mul_lo_u32 v8, v5, s44
	v_lshlrev_b32_e32 v10, 2, v1
	v_add_u32_e32 v19, v8, v1
	v_add_u32_e32 v14, s45, v10
	v_lshl_add_u32 v178, v19, 2, s46
	v_add_u32_e32 v19, 0x44, v8
	v_add_u32_e32 v20, v19, v1
	v_lshl_add_u32 v181, v19, 2, v14
	v_add_u32_e32 v19, 0x88, v8
	v_lshl_add_u32 v180, v20, 2, s46
	v_add_u32_e32 v20, v19, v1
	v_lshl_add_u32 v183, v19, 2, v14
	v_add_u32_e32 v19, 0xcc, v8
	v_lshl_add_u32 v182, v20, 2, s46
	v_add_u32_e32 v20, v19, v1
	v_lshl_add_u32 v185, v19, 2, v14
	v_add_u32_e32 v19, 0x110, v8
	v_lshl_add_u32 v184, v20, 2, s46
	v_add_u32_e32 v20, v19, v1
	v_lshl_add_u32 v187, v19, 2, v14
	v_add_u32_e32 v19, 0x154, v8
	v_lshl_add_u32 v186, v20, 2, s46
	v_add_u32_e32 v20, v19, v1
	v_lshl_add_u32 v189, v19, 2, v14
	v_add_u32_e32 v19, 0x198, v8
	v_lshl_add_u32 v188, v20, 2, s46
	v_add_u32_e32 v20, v19, v1
	v_lshl_add_u32 v191, v19, 2, v14
	v_add_u32_e32 v19, 0x1dc, v8
	v_lshl_add_u32 v190, v20, 2, s46
	v_add_u32_e32 v20, v19, v1
	v_lshl_add_u32 v193, v19, 2, v14
	v_add_u32_e32 v19, 0x220, v8
	v_lshl_add_u32 v192, v20, 2, s46
	v_add_u32_e32 v20, v19, v1
	v_lshl_add_u32 v195, v19, 2, v14
	v_add_u32_e32 v19, 0x264, v8
	v_lshl_add_u32 v194, v20, 2, s46
	v_add_u32_e32 v20, v19, v1
	v_lshl_add_u32 v197, v19, 2, v14
	v_add_u32_e32 v19, 0x2a8, v8
	v_lshl_add_u32 v196, v20, 2, s46
	v_add_u32_e32 v20, v19, v1
	v_lshl_add_u32 v199, v19, 2, v14
	v_add_u32_e32 v19, 0x2ec, v8
	s_load_dwordx4 s[36:39], s[34:35], 0xd8
	v_lshl_add_u32 v198, v20, 2, s46
	v_add_u32_e32 v20, v19, v1
	v_lshl_add_u32 v201, v19, 2, v14
	v_add_u32_e32 v19, 0x330, v8
	v_add_u32_e32 v145, 0x400, v126
	v_ashrrev_i32_e32 v7, 2, v126
	v_add_u32_e32 v18, 0x600, v126
	v_lshl_add_u32 v179, v8, 2, v14
	v_lshl_add_u32 v200, v20, 2, s46
	v_add_u32_e32 v20, v19, v1
	v_lshl_add_u32 v203, v19, 2, v14
	v_add_u32_e32 v19, 0x374, v8
	v_add_u32_e32 v8, 0x3b8, v8
	v_and_b32_e32 v9, -4, v7
	v_and_b32_e32 v155, 48, v126
	v_ashrrev_i32_e32 v158, 4, v126
	v_ashrrev_i32_e32 v160, 4, v145
	v_ashrrev_i32_e32 v161, 4, v18
	v_cmp_lt_i32_e64 s[18:19], 3, v7
	v_cmp_lt_i32_e64 s[20:21], -1, v7
	v_or_b32_e32 v7, 3, v7
	v_ashrrev_i32_e32 v134, 3, v126
	v_lshl_add_u32 v202, v20, 2, s46
	v_add_u32_e32 v20, v19, v1
	v_lshl_add_u32 v205, v19, 2, v14
	v_add_u32_e32 v19, v8, v1
	s_movk_i32 s44, 0x1100
	v_lshlrev_b32_e32 v148, 3, v3
	v_add_u32_e32 v130, -3, v9
	v_lshl_add_u32 v11, v3, 4, s6
	v_add_u32_e32 v152, 0x7d, v9
	v_add_u32_e32 v12, s6, v155
	v_lshl_add_u32 v15, v153, 2, s45
	v_mul_lo_u32 v4, v158, s47
	v_mul_lo_u32 v16, v159, s47
	v_mul_lo_u32 v17, v160, s47
	v_mul_lo_u32 v18, v161, s47
	v_cmp_lt_i32_e64 s[22:23], -2, v9
	v_cmp_lt_i32_e64 s[24:25], -3, v9
	v_mul_lo_u32 v9, v9, s47
	v_mul_lo_u32 v7, v7, s47
	v_mul_u32_u24_e32 v3, 0x110, v3
	v_lshl_add_u32 v204, v20, 2, s46
	v_lshl_add_u32 v206, v19, 2, s46
	v_lshl_add_u32 v207, v8, 2, v14
	v_mul_lo_u32 v8, v144, s44
	v_mul_lo_u32 v5, v5, s47
	v_mul_lo_u32 v19, v134, s47
	v_mul_lo_u32 v20, v136, s47
	v_cmp_gt_i32_e64 s[4:5], 64, v126
	v_or_b32_e32 v149, 0x400, v148
	v_or_b32_e32 v150, 0x1000, v148
	v_ashrrev_i32_e32 v131, 31, v130
	v_add_u32_e32 v151, s64, v10
	v_cmp_lt_i32_e64 s[6:7], 0, v144
	v_cmp_eq_u32_e64 s[8:9], 7, v144
	v_ashrrev_i32_e32 v127, 31, v126
	v_cmp_gt_i32_e64 s[10:11], 64, v158
	v_cmp_gt_i32_e64 s[12:13], 64, v159
	v_cmp_gt_i32_e64 s[14:15], 64, v160
	v_cmp_gt_i32_e64 s[16:17], 64, v161
	v_ashrrev_i32_e32 v135, 31, v134
	v_ashrrev_i32_e32 v137, 31, v136
	v_lshl_add_u32 v208, v13, 1, v154
	v_add_u32_e32 v209, s40, v10
	v_add_u32_e32 v210, v6, v4
	v_add_u32_e32 v211, v6, v16
	v_add_u32_e32 v212, v6, v17
	v_add_u32_e32 v213, v6, v18
	s_mov_b64 s[44:45], 0x1000
	s_mov_b64 s[46:47], 0x2000
	s_mov_b64 s[48:49], 0x3000
	v_add_u32_e32 v214, v11, v9
	v_add_u32_e32 v215, v11, v7
	v_add_u32_e32 v216, v12, v3
	s_mov_b32 s65, 0xbecccccd
	v_mov_b32_e32 v217, 0x3c088889
	v_add_u32_e32 v218, v14, v8
	v_add_u32_e32 v219, v14, v5
	v_add_u32_e32 v220, v15, v19
	v_add_u32_e32 v221, v15, v20
	s_mov_b32 s66, s33
	s_branch .LBB0_3836
